# seams 5,12: one overlay-protecting L2 write-back per co-XCD panel group (member 0) instead of one per workgroup
# baseline (speedup 1.0000x reference)
.LBB0_1128:
	s_andn2_b64 vcc, exec, s[0:1]
	s_cbranch_vccnz .LBB0_1195
	v_readlane_b32 s0, v249, 4
	v_readlane_b32 s1, v249, 5
	s_cmpk_lt_u32 s1, 0x3e9
	s_mov_b64 s[0:1], -1
	s_cbranch_scc0 .LBB0_1183
	v_readlane_b32 s2, v249, 2
	s_cmpk_eq_i32 s2, 0x100
	s_cbranch_scc0 .Lg5_xcd
	s_waitcnt vmcnt(0)
	s_waitcnt vmcnt(0) lgkmcnt(0)
	s_barrier
	s_mov_b64 s[0:1], exec
	v_readlane_b32 s2, v249, 10
	v_readlane_b32 s3, v249, 11
	s_and_b64 s[2:3], s[0:1], s[2:3]
	s_mov_b64 exec, s[2:3]
	s_cbranch_execz .Lg5_BB0_1004
	s_lshl_b32 s2, s81, 8
	s_and_b32 s2, s2, 0x3f00
	s_mov_b64 s[4:5], exec
	s_add_u32 s2, s82, s2
	s_addc_u32 s3, s83, 0
	v_readlane_b32 s98, v250, 0
	s_cmp_lg_u32 s98, 0
	s_cselect_b32 s98, 1, 0
	s_lshr_b32 s99, s81, 6
	s_cmp_lg_u32 s99, 0
	s_cselect_b32 s99, 1, 0
	s_and_b32 s98, s98, s99
	s_cbranch_scc1 .Lg5_skip_wbl2_2
	buffer_wbl2 sc1
